# code placement: attention loop back-edge targets aligned to 64 B (pad never executed)
# baseline (speedup 1.0000x reference)
.Lat1_resc_b:
	v_mov_b32_e32 v52, v51
	s_nop 1
	v_permlane32_swap_b32_e32 v51, v52
	v_max_f32_e32 v51, v51, v52
	v_max_f32_e32 v34, v51, v51
	v_max_f32_e32 v35, 0, v34
	v_exp_f32_e64 v36, -v35
	v_mov_b32_e32 v34, v35
	v_add_f32_e32 v205, v204, v35
	v_pk_add_f32 v[82:83], v[82:83], v[34:35] op_sel_hi:[1,0] neg_lo:[0,1] neg_hi:[0,1]
	v_pk_add_f32 v[98:99], v[98:99], v[34:35] op_sel_hi:[1,0] neg_lo:[0,1] neg_hi:[0,1]
	v_pk_add_f32 v[84:85], v[84:85], v[34:35] op_sel_hi:[1,0] neg_lo:[0,1] neg_hi:[0,1]
	v_pk_add_f32 v[100:101], v[100:101], v[34:35] op_sel_hi:[1,0] neg_lo:[0,1] neg_hi:[0,1]
	v_pk_add_f32 v[86:87], v[86:87], v[34:35] op_sel_hi:[1,0] neg_lo:[0,1] neg_hi:[0,1]
	v_pk_add_f32 v[102:103], v[102:103], v[34:35] op_sel_hi:[1,0] neg_lo:[0,1] neg_hi:[0,1]
	v_pk_add_f32 v[88:89], v[88:89], v[34:35] op_sel_hi:[1,0] neg_lo:[0,1] neg_hi:[0,1]
	v_pk_add_f32 v[104:105], v[104:105], v[34:35] op_sel_hi:[1,0] neg_lo:[0,1] neg_hi:[0,1]
	v_pk_add_f32 v[90:91], v[90:91], v[34:35] op_sel_hi:[1,0] neg_lo:[0,1] neg_hi:[0,1]
	v_pk_add_f32 v[106:107], v[106:107], v[34:35] op_sel_hi:[1,0] neg_lo:[0,1] neg_hi:[0,1]
	v_pk_add_f32 v[92:93], v[92:93], v[34:35] op_sel_hi:[1,0] neg_lo:[0,1] neg_hi:[0,1]
	v_pk_add_f32 v[108:109], v[108:109], v[34:35] op_sel_hi:[1,0] neg_lo:[0,1] neg_hi:[0,1]
	v_pk_add_f32 v[94:95], v[94:95], v[34:35] op_sel_hi:[1,0] neg_lo:[0,1] neg_hi:[0,1]
	v_pk_add_f32 v[110:111], v[110:111], v[34:35] op_sel_hi:[1,0] neg_lo:[0,1] neg_hi:[0,1]
	v_pk_add_f32 v[96:97], v[96:97], v[34:35] op_sel_hi:[1,0] neg_lo:[0,1] neg_hi:[0,1]
	v_pk_add_f32 v[112:113], v[112:113], v[34:35] op_sel_hi:[1,0] neg_lo:[0,1] neg_hi:[0,1]
	v_xor_b32_e32 v34, 0x80000000, v205
	v_pk_mul_f32 v[16:17], v[16:17], v[36:37] op_sel_hi:[1,0]
	v_pk_mul_f32 v[14:15], v[14:15], v[36:37] op_sel_hi:[1,0]
	v_pk_mul_f32 v[12:13], v[12:13], v[36:37] op_sel_hi:[1,0]
	v_pk_mul_f32 v[10:11], v[10:11], v[36:37] op_sel_hi:[1,0]
	v_pk_mul_f32 v[8:9], v[8:9], v[36:37] op_sel_hi:[1,0]
	v_pk_mul_f32 v[6:7], v[6:7], v[36:37] op_sel_hi:[1,0]
	v_pk_mul_f32 v[4:5], v[4:5], v[36:37] op_sel_hi:[1,0]
	v_pk_mul_f32 v[2:3], v[2:3], v[36:37] op_sel_hi:[1,0]
	v_pk_mul_f32 v[32:33], v[32:33], v[36:37] op_sel_hi:[1,0]
	v_pk_mul_f32 v[30:31], v[30:31], v[36:37] op_sel_hi:[1,0]
	v_pk_mul_f32 v[28:29], v[28:29], v[36:37] op_sel_hi:[1,0]
	v_pk_mul_f32 v[26:27], v[26:27], v[36:37] op_sel_hi:[1,0]
	v_pk_mul_f32 v[24:25], v[24:25], v[36:37] op_sel_hi:[1,0]
	v_pk_mul_f32 v[22:23], v[22:23], v[36:37] op_sel_hi:[1,0]
	v_pk_mul_f32 v[20:21], v[20:21], v[36:37] op_sel_hi:[1,0]
	v_pk_mul_f32 v[18:19], v[18:19], v[36:37] op_sel_hi:[1,0]
	v_mul_f32_e32 v180, v180, v36
	v_mov_b32_e32 v35, v34
	v_mov_b32_e32 v36, v34
	v_mov_b32_e32 v37, v34
	v_mov_b32_e32 v38, v34
	v_mov_b32_e32 v39, v34
	v_mov_b32_e32 v40, v34
	v_mov_b32_e32 v41, v34
	v_mov_b32_e32 v42, v34
	v_mov_b32_e32 v43, v34
	v_mov_b32_e32 v44, v34
	v_mov_b32_e32 v45, v34
	v_mov_b32_e32 v46, v34
	v_mov_b32_e32 v47, v34
	v_mov_b32_e32 v48, v34
	v_mov_b32_e32 v49, v34
	s_branch .LBB0_820
	.p2alignl 6, 3212836864

.Lat2_resc_b:
	v_mov_b32_e32 v4, v3
	s_nop 1
	v_permlane32_swap_b32_e32 v3, v4
	v_max_f32_e32 v3, v3, v4
	v_max_f32_e32 v3, v3, v3
	v_max_f32_e32 v3, 0, v3
	v_exp_f32_e64 v4, -v3
	v_add_f32_e32 v210, v209, v3
	v_mov_b32_e32 v2, v3
	v_xor_b32_e32 v48, 0x80000000, v210
	v_pk_add_f32 v[96:97], v[96:97], v[2:3] op_sel_hi:[1,0] neg_lo:[0,1] neg_hi:[0,1]
	v_pk_add_f32 v[112:113], v[112:113], v[2:3] op_sel_hi:[1,0] neg_lo:[0,1] neg_hi:[0,1]
	v_pk_add_f32 v[98:99], v[98:99], v[2:3] op_sel_hi:[1,0] neg_lo:[0,1] neg_hi:[0,1]
	v_pk_add_f32 v[114:115], v[114:115], v[2:3] op_sel_hi:[1,0] neg_lo:[0,1] neg_hi:[0,1]
	v_pk_add_f32 v[100:101], v[100:101], v[2:3] op_sel_hi:[1,0] neg_lo:[0,1] neg_hi:[0,1]
	v_pk_add_f32 v[116:117], v[116:117], v[2:3] op_sel_hi:[1,0] neg_lo:[0,1] neg_hi:[0,1]
	v_pk_add_f32 v[102:103], v[102:103], v[2:3] op_sel_hi:[1,0] neg_lo:[0,1] neg_hi:[0,1]
	v_pk_add_f32 v[118:119], v[118:119], v[2:3] op_sel_hi:[1,0] neg_lo:[0,1] neg_hi:[0,1]
	v_pk_add_f32 v[104:105], v[104:105], v[2:3] op_sel_hi:[1,0] neg_lo:[0,1] neg_hi:[0,1]
	v_pk_add_f32 v[120:121], v[120:121], v[2:3] op_sel_hi:[1,0] neg_lo:[0,1] neg_hi:[0,1]
	v_pk_add_f32 v[106:107], v[106:107], v[2:3] op_sel_hi:[1,0] neg_lo:[0,1] neg_hi:[0,1]
	v_pk_add_f32 v[122:123], v[122:123], v[2:3] op_sel_hi:[1,0] neg_lo:[0,1] neg_hi:[0,1]
	v_pk_add_f32 v[108:109], v[108:109], v[2:3] op_sel_hi:[1,0] neg_lo:[0,1] neg_hi:[0,1]
	v_pk_add_f32 v[124:125], v[124:125], v[2:3] op_sel_hi:[1,0] neg_lo:[0,1] neg_hi:[0,1]
	v_pk_add_f32 v[110:111], v[110:111], v[2:3] op_sel_hi:[1,0] neg_lo:[0,1] neg_hi:[0,1]
	v_pk_add_f32 v[126:127], v[126:127], v[2:3] op_sel_hi:[1,0] neg_lo:[0,1] neg_hi:[0,1]
	v_pk_mul_f32 v[46:47], v[46:47], v[4:5] op_sel_hi:[1,0]
	v_pk_mul_f32 v[44:45], v[44:45], v[4:5] op_sel_hi:[1,0]
	v_pk_mul_f32 v[42:43], v[42:43], v[4:5] op_sel_hi:[1,0]
	v_pk_mul_f32 v[40:41], v[40:41], v[4:5] op_sel_hi:[1,0]
	v_pk_mul_f32 v[38:39], v[38:39], v[4:5] op_sel_hi:[1,0]
	v_pk_mul_f32 v[36:37], v[36:37], v[4:5] op_sel_hi:[1,0]
	v_pk_mul_f32 v[34:35], v[34:35], v[4:5] op_sel_hi:[1,0]
	v_pk_mul_f32 v[32:33], v[32:33], v[4:5] op_sel_hi:[1,0]
	v_pk_mul_f32 v[30:31], v[30:31], v[4:5] op_sel_hi:[1,0]
	v_pk_mul_f32 v[28:29], v[28:29], v[4:5] op_sel_hi:[1,0]
	v_pk_mul_f32 v[26:27], v[26:27], v[4:5] op_sel_hi:[1,0]
	v_pk_mul_f32 v[24:25], v[24:25], v[4:5] op_sel_hi:[1,0]
	v_pk_mul_f32 v[22:23], v[22:23], v[4:5] op_sel_hi:[1,0]
	v_pk_mul_f32 v[20:21], v[20:21], v[4:5] op_sel_hi:[1,0]
	v_pk_mul_f32 v[18:19], v[18:19], v[4:5] op_sel_hi:[1,0]
	v_pk_mul_f32 v[16:17], v[16:17], v[4:5] op_sel_hi:[1,0]
	v_mul_f32_e32 v188, v188, v4
	v_mov_b32_e32 v49, v48
	v_mov_b32_e32 v50, v48
	v_mov_b32_e32 v51, v48
	v_mov_b32_e32 v52, v48
	v_mov_b32_e32 v53, v48
	v_mov_b32_e32 v54, v48
	v_mov_b32_e32 v55, v48
	v_mov_b32_e32 v56, v48
	v_mov_b32_e32 v57, v48
	v_mov_b32_e32 v58, v48
	v_mov_b32_e32 v59, v48
	v_mov_b32_e32 v60, v48
	v_mov_b32_e32 v61, v48
	v_mov_b32_e32 v62, v48
	v_mov_b32_e32 v63, v48
	s_branch .LBB0_875
	.p2alignl 6, 3212836864
